# attention tile loops: first PV MFMAs (ks=0, ks=2) hoisted into the exp chain of the same tile for in-body MFMA/VALU overlap (5 of 6 loop tiles)
# baseline (speedup 1.0000x reference)
; __device__ __forceinline__ unsigned pk2(float lo, float hi) { f32x2 v = {lo, hi}; bf16x2_t b = __builtin_convertvector(v, bf16x2_t); return __builtin_bit_cast(unsigned, b); }
; __device__ __forceinline__ float hsum(float m) { auto rr = __builtin_amdgcn_permlane32_swap(__float_as_uint(m), __float_as_uint(m), false, false); return __uint_as_float(rr[0]) + __uint_as_float(rr[1]); }
; template <int TYPE, int ND0, int KSTR> __device__ __forceinline__ void tile(LAS unsigned char* lds, int buf, int t, int w_lo, int w_hi, int n, int qrel, int lane, int r32, int hi,
;         const bf16x8 (&qr)[ND0], float& m_run, float& l_run, f32x16& o0, f32x16& o1, f32x16& negm) {
;     ...
;     float ls = 0.f;
; #pragma unroll
;     for (int r = 0; r < 16; ++r) { p0[r] = __builtin_amdgcn_exp2f(p0[r]); p1[r] = __builtin_amdgcn_exp2f(p1[r]); ls += p0[r] + p1[r]; }
;     const float lrow = hsum(ls);
;     ...
; #pragma unroll
;     for (int ks = 0; ks < 4; ++ks) {
;         u32x4 pw;
;         if (ks < 2) { pw.x = pk2(p0[8 * ks], p0[8 * ks + 1]); pw.y = pk2(p0[8 * ks + 2], p0[8 * ks + 3]); pw.z = pk2(p0[8 * ks + 4], p0[8 * ks + 5]); pw.w = pk2(p0[8 * ks + 6], p0[8 * ks + 7]); }
;         else { const int k2 = ks - 2; pw.x = pk2(p1[8 * k2], p1[8 * k2 + 1]); pw.y = pk2(p1[8 * k2 + 2], p1[8 * k2 + 3]); pw.z = pk2(p1[8 * k2 + 4], p1[8 * k2 + 5]); pw.w = pk2(p1[8 * k2 + 6], p1[8 * k2 + 7]); }
;         const bf16x8 pb = __builtin_bit_cast(bf16x8, pw);
;         const bf16x8 va0 = __builtin_shufflevector(vf[ks][0], vf[ks][1], 0, 1, 2, 3, 4, 5, 6, 7), va1 = __builtin_shufflevector(vf[ks][2], vf[ks][3], 0, 1, 2, 3, 4, 5, 6, 7);
;         o0 = __builtin_amdgcn_mfma_f32_32x32x16_bf16(va0, pb, o0, 0, 0, 0);
;         o1 = __builtin_amdgcn_mfma_f32_32x32x16_bf16(va1, pb, o1, 0, 0, 0);
;     }
.LBB0_614:
	s_nop 7
	v_exp_f32_e32 v80, v80
	v_exp_f32_e32 v14, v64
	v_exp_f32_e32 v0, v81
	v_exp_f32_e32 v174, v65
	v_exp_f32_e32 v82, v82
	v_add_f32_e32 v175, v14, v80
	v_exp_f32_e32 v176, v67
	v_pk_add_f32 v[64:65], v[174:175], v[0:1]
	v_exp_f32_e32 v84, v84
	v_pk_add_f32 v[188:189], v[64:65], v[64:65] op_sel_hi:[0,1]
	v_exp_f32_e32 v64, v66
	v_exp_f32_e32 v188, v83
	v_exp_f32_e32 v178, v69
	v_exp_f32_e32 v172, v86
	v_add_f32_e32 v177, v64, v82
	v_pk_add_f32 v[66:67], v[176:177], v[188:189]
	v_exp_f32_e32 v70, v70
	v_pk_add_f32 v[190:191], v[66:67], v[66:67] op_sel_hi:[0,1]
	v_exp_f32_e32 v66, v68
	v_exp_f32_e32 v190, v85
	v_exp_f32_e32 v182, v71
	v_add_f32_e32 v183, v70, v172
	v_add_f32_e32 v179, v66, v84
	v_pk_add_f32 v[68:69], v[178:179], v[190:191]
	v_exp_f32_e32 v86, v88
	v_pk_add_f32 v[194:195], v[68:69], v[68:69] op_sel_hi:[0,1]
	v_exp_f32_e32 v194, v87
	v_cvt_pk_bf16_f32 v96, v80, v0
	v_cvt_pk_bf16_f32 v97, v82, v188
	v_cvt_pk_bf16_f32 v98, v84, v190
	v_cvt_pk_bf16_f32 v99, v172, v194
	v_cvt_pk_bf16_f32 v100, v14, v174
	v_cvt_pk_bf16_f32 v101, v64, v176
	v_cvt_pk_bf16_f32 v102, v66, v178
	v_cvt_pk_bf16_f32 v103, v70, v182
	v_mfma_f32_32x32x16_bf16 v[32:47], v[164:167], v[96:99], v[32:47]
	s_waitcnt lgkmcnt(12)
	v_mfma_f32_32x32x16_bf16 v[16:31], v[168:171], v[96:99], v[16:31]
	s_waitcnt lgkmcnt(6)
	v_mfma_f32_32x32x16_bf16 v[32:47], v[148:151], v[100:103], v[32:47]
	s_waitcnt lgkmcnt(4)
	v_mfma_f32_32x32x16_bf16 v[16:31], v[152:155], v[100:103], v[16:31]
	v_exp_f32_e32 v180, v73
	v_exp_f32_e32 v88, v90
	v_exp_f32_e32 v184, v75
	v_pk_add_f32 v[68:69], v[182:183], v[194:195]
	v_exp_f32_e32 v90, v92
	v_pk_add_f32 v[192:193], v[68:69], v[68:69] op_sel_hi:[0,1]
	v_exp_f32_e32 v68, v72
	v_exp_f32_e32 v192, v89
	v_exp_f32_e32 v186, v77
	v_exp_f32_e32 v92, v94
	v_add_f32_e32 v181, v68, v86
	v_pk_add_f32 v[72:73], v[180:181], v[192:193]
	s_mov_b32 s3, 0x53800000
	v_pk_add_f32 v[196:197], v[72:73], v[72:73] op_sel_hi:[0,1]
	v_exp_f32_e32 v72, v74
	v_exp_f32_e32 v196, v91
	v_add_f32_e32 v185, v72, v88
	v_pk_add_f32 v[74:75], v[184:185], v[196:197]
	s_nop 0
	v_pk_add_f32 v[198:199], v[74:75], v[74:75] op_sel_hi:[0,1]
	v_exp_f32_e32 v74, v76
	v_exp_f32_e32 v198, v93
	v_add_f32_e32 v187, v74, v90
	v_pk_add_f32 v[76:77], v[186:187], v[198:199]
	s_nop 0
	v_pk_add_f32 v[200:201], v[76:77], v[76:77] op_sel_hi:[0,1]
	v_exp_f32_e32 v76, v78
	v_exp_f32_e32 v200, v95
	v_exp_f32_e32 v78, v79
	v_add_f32_e32 v79, v76, v92
	v_pk_add_f32 v[94:95], v[78:79], v[200:201]
	s_nop 0
	v_pk_add_f32 v[94:95], v[94:95], v[94:95] op_sel:[0,1] op_sel_hi:[1,0]
	s_nop 0
	v_mov_b32_e32 v15, v94
	v_mov_b32_e32 v65, v94
	s_nop 1
	v_permlane32_swap_b32_e32 v15, v65
	v_add_f32_e32 v15, v15, v65
	v_cmp_lt_f32_e32 vcc, s3, v15
	s_cbranch_vccz .LBB0_616
; __device__ __forceinline__ unsigned pk2(float lo, float hi) { f32x2 v = {lo, hi}; bf16x2_t b = __builtin_convertvector(v, bf16x2_t); return __builtin_bit_cast(unsigned, b); }
; __device__ __forceinline__ float hmax(float m) { auto rr = __builtin_amdgcn_permlane32_swap(__float_as_uint(m), __float_as_uint(m), false, false); return fmaxf(__uint_as_float(rr[0]), __uint_as_float(rr[1])); }
; template <int TYPE, int ND0, int KSTR> __device__ __forceinline__ void tile(LAS unsigned char* lds, int buf, int t, int w_lo, int w_hi, int n, int qrel, int lane, int r32, int hi,
;         const bf16x8 (&qr)[ND0], float& m_run, float& l_run, f32x16& o0, f32x16& o1, f32x16& negm) {
;     ...
;     if (__builtin_amdgcn_ballot_w64(lrow > 1099511627776.0f) != 0ull) {
;         float pm = fmaxf(p0[0], p1[0]);
; #pragma unroll
;         for (int r = 1; r < 16; ++r) pm = fmaxf(pm, fmaxf(p0[r], p1[r]));
;         pm = hmax(pm);
;         const float dl = (lrow > 1099511627776.0f) ? __builtin_amdgcn_logf(pm) : 0.f;
;         const float sc = __builtin_amdgcn_exp2f(-dl);
;         m_run += dl; l_run *= sc; ls *= sc;
; #pragma unroll
;         for (int r = 0; r < 16; ++r) { p0[r] *= sc; p1[r] *= sc; o0[r] *= sc; o1[r] *= sc; negm[r] = -m_run; }
;     }
;     l_run += ls;
; #pragma unroll
;     for (int ks = 0; ks < 4; ++ks) {
;         u32x4 pw;
;         if (ks < 2) { pw.x = pk2(p0[8 * ks], p0[8 * ks + 1]); pw.y = pk2(p0[8 * ks + 2], p0[8 * ks + 3]); pw.z = pk2(p0[8 * ks + 4], p0[8 * ks + 5]); pw.w = pk2(p0[8 * ks + 6], p0[8 * ks + 7]); }
;         else { const int k2 = ks - 2; pw.x = pk2(p1[8 * k2], p1[8 * k2 + 1]); pw.y = pk2(p1[8 * k2 + 2], p1[8 * k2 + 3]); pw.z = pk2(p1[8 * k2 + 4], p1[8 * k2 + 5]); pw.w = pk2(p1[8 * k2 + 6], p1[8 * k2 + 7]); }
;         const bf16x8 pb = __builtin_bit_cast(bf16x8, pw);
;         const bf16x8 va0 = __builtin_shufflevector(vf[ks][0], vf[ks][1], 0, 1, 2, 3, 4, 5, 6, 7), va1 = __builtin_shufflevector(vf[ks][2], vf[ks][3], 0, 1, 2, 3, 4, 5, 6, 7);
;         o0 = __builtin_amdgcn_mfma_f32_32x32x16_bf16(va0, pb, o0, 0, 0, 0);
;         o1 = __builtin_amdgcn_mfma_f32_32x32x16_bf16(va1, pb, o1, 0, 0, 0);
;     }
	v_max_f32_e32 v15, v174, v174
	v_max_f32_e32 v48, v0, v0
	v_max_f32_e32 v15, v48, v15
	v_max_f32_e32 v48, v64, v64
	v_max_f32_e32 v49, v82, v82
	v_max_f32_e32 v48, v49, v48
	v_max_f32_e32 v49, v176, v176
	v_max_f32_e32 v50, v188, v188
	v_max3_f32 v15, v80, v14, v15
	v_max_f32_e32 v49, v50, v49
	v_max3_f32 v15, v15, v48, v49
	v_max_f32_e32 v48, v66, v66
	v_max_f32_e32 v49, v84, v84
	v_max_f32_e32 v48, v49, v48
	v_max_f32_e32 v49, v178, v178
	v_max_f32_e32 v50, v190, v190
	v_max_f32_e32 v49, v50, v49
	v_max3_f32 v15, v15, v48, v49
	v_max_f32_e32 v48, v70, v70
	v_max_f32_e32 v49, v172, v172
	v_max_f32_e32 v48, v49, v48
	v_max_f32_e32 v49, v182, v182
	v_max_f32_e32 v50, v194, v194
	v_max_f32_e32 v49, v50, v49
	v_max3_f32 v15, v15, v48, v49
	v_max_f32_e32 v48, v68, v68
	v_max_f32_e32 v49, v86, v86
	v_max_f32_e32 v48, v49, v48
	v_max_f32_e32 v49, v180, v180
	v_max_f32_e32 v50, v192, v192
	v_max_f32_e32 v49, v50, v49
	v_max3_f32 v15, v15, v48, v49
	v_max_f32_e32 v48, v72, v72
	v_max_f32_e32 v49, v88, v88
	v_max_f32_e32 v48, v49, v48
	v_max_f32_e32 v49, v184, v184
	v_max_f32_e32 v50, v196, v196
	v_max_f32_e32 v49, v50, v49
	v_max3_f32 v15, v15, v48, v49
	v_max_f32_e32 v48, v74, v74
	v_max_f32_e32 v49, v90, v90
	v_max_f32_e32 v48, v49, v48
	v_max_f32_e32 v49, v186, v186
	v_max_f32_e32 v50, v198, v198
	v_max_f32_e32 v49, v50, v49
	v_max3_f32 v15, v15, v48, v49
	v_max_f32_e32 v48, v76, v76
	v_max_f32_e32 v49, v92, v92
	v_max_f32_e32 v48, v49, v48
	v_max_f32_e32 v49, v78, v78
	v_max_f32_e32 v50, v200, v200
	v_max_f32_e32 v49, v50, v49
	v_max3_f32 v15, v15, v48, v49
	v_mov_b32_e32 v48, v15
	s_nop 1
	v_permlane32_swap_b32_e32 v15, v48
	v_max_f32_e32 v48, v48, v48
	v_max_f32_e32 v15, v15, v15
	v_max_f32_e32 v15, v15, v48
	v_log_f32_e32 v15, v15
	v_mov_b32_e32 v223, v94
	v_mov_b32_e32 v93, v200
	v_mov_b32_e32 v91, v198
	v_cndmask_b32_e32 v15, 0, v15, vcc
	v_exp_f32_e64 v94, -v15
	v_add_f32_e32 v225, v225, v15
	v_mov_b32_e32 v89, v196
	v_mov_b32_e32 v87, v192
	v_mov_b32_e32 v173, v194
	v_mov_b32_e32 v85, v190
	v_mov_b32_e32 v83, v188
	v_mov_b32_e32 v81, v0
	v_mov_b32_e32 v77, v78
	v_mov_b32_e32 v75, v186
	v_mov_b32_e32 v73, v184
	v_mov_b32_e32 v69, v180
	v_mov_b32_e32 v71, v182
	v_mov_b32_e32 v67, v178
	v_mov_b32_e32 v65, v176
	v_mov_b32_e32 v15, v174
	v_xor_b32_e32 v48, 0x80000000, v225
	v_pk_mul_f32 v[92:93], v[92:93], v[94:95] op_sel_hi:[1,0]
	v_pk_mul_f32 v[90:91], v[90:91], v[94:95] op_sel_hi:[1,0]
	v_pk_mul_f32 v[88:89], v[88:89], v[94:95] op_sel_hi:[1,0]
	v_pk_mul_f32 v[86:87], v[86:87], v[94:95] op_sel_hi:[1,0]
	v_pk_mul_f32 v[172:173], v[172:173], v[94:95] op_sel_hi:[1,0]
	v_pk_mul_f32 v[84:85], v[84:85], v[94:95] op_sel_hi:[1,0]
	v_pk_mul_f32 v[82:83], v[82:83], v[94:95] op_sel_hi:[1,0]
	v_pk_mul_f32 v[80:81], v[80:81], v[94:95] op_sel_hi:[1,0]
	v_pk_mul_f32 v[76:77], v[76:77], v[94:95] op_sel_hi:[1,0]
	v_pk_mul_f32 v[74:75], v[74:75], v[94:95] op_sel_hi:[1,0]
	v_pk_mul_f32 v[72:73], v[72:73], v[94:95] op_sel_hi:[1,0]
	v_pk_mul_f32 v[68:69], v[68:69], v[94:95] op_sel_hi:[1,0]
	v_pk_mul_f32 v[70:71], v[70:71], v[94:95] op_sel_hi:[1,0]
	v_pk_mul_f32 v[66:67], v[66:67], v[94:95] op_sel_hi:[1,0]
	v_pk_mul_f32 v[64:65], v[64:65], v[94:95] op_sel_hi:[1,0]
	v_pk_mul_f32 v[14:15], v[14:15], v[94:95] op_sel_hi:[1,0]
	v_pk_mul_f32 v[222:223], v[222:223], v[94:95] op_sel_hi:[1,0]
	v_pk_mul_f32 v[46:47], v[46:47], v[94:95] op_sel_hi:[1,0]
	v_pk_mul_f32 v[44:45], v[44:45], v[94:95] op_sel_hi:[1,0]
	v_pk_mul_f32 v[42:43], v[42:43], v[94:95] op_sel_hi:[1,0]
	v_pk_mul_f32 v[40:41], v[40:41], v[94:95] op_sel_hi:[1,0]
	v_pk_mul_f32 v[38:39], v[38:39], v[94:95] op_sel_hi:[1,0]
	v_pk_mul_f32 v[36:37], v[36:37], v[94:95] op_sel_hi:[1,0]
	v_pk_mul_f32 v[34:35], v[34:35], v[94:95] op_sel_hi:[1,0]
	v_pk_mul_f32 v[32:33], v[32:33], v[94:95] op_sel_hi:[1,0]
	v_pk_mul_f32 v[30:31], v[30:31], v[94:95] op_sel_hi:[1,0]
	v_pk_mul_f32 v[28:29], v[28:29], v[94:95] op_sel_hi:[1,0]
	v_pk_mul_f32 v[26:27], v[26:27], v[94:95] op_sel_hi:[1,0]
	v_pk_mul_f32 v[24:25], v[24:25], v[94:95] op_sel_hi:[1,0]
	v_pk_mul_f32 v[22:23], v[22:23], v[94:95] op_sel_hi:[1,0]
	v_pk_mul_f32 v[20:21], v[20:21], v[94:95] op_sel_hi:[1,0]
	v_pk_mul_f32 v[18:19], v[18:19], v[94:95] op_sel_hi:[1,0]
	v_pk_mul_f32 v[16:17], v[16:17], v[94:95] op_sel_hi:[1,0]
	v_mov_b32_e32 v49, v48
	v_mov_b32_e32 v50, v48
	v_mov_b32_e32 v51, v48
	v_mov_b32_e32 v52, v48
	v_mov_b32_e32 v53, v48
	v_mov_b32_e32 v54, v48
	v_mov_b32_e32 v55, v48
	v_mov_b32_e32 v56, v48
	v_mov_b32_e32 v57, v48
	v_mov_b32_e32 v58, v48
	v_mov_b32_e32 v59, v48
	v_mov_b32_e32 v60, v48
	v_mov_b32_e32 v61, v48
	v_mov_b32_e32 v62, v48
	v_mov_b32_e32 v63, v48
	v_mov_b32_e32 v174, v15
	v_mov_b32_e32 v176, v65
	v_mov_b32_e32 v178, v67
	v_mov_b32_e32 v182, v71
	v_mov_b32_e32 v180, v69
	v_mov_b32_e32 v184, v73
	v_mov_b32_e32 v186, v75
	v_mov_b32_e32 v78, v77
	v_mov_b32_e32 v0, v81
	v_mov_b32_e32 v188, v83
	v_mov_b32_e32 v190, v85
	v_mov_b32_e32 v194, v173
	v_mov_b32_e32 v192, v87
	v_mov_b32_e32 v196, v89
	v_mov_b32_e32 v198, v91
	v_mov_b32_e32 v200, v93
	v_mov_b32_e32 v94, v223
.LBB0_616:
	v_cvt_pk_bf16_f32 v65, v72, v184
	v_cvt_pk_bf16_f32 v67, v76, v78
	v_add_f32_e32 v222, v222, v94
	v_cvt_pk_bf16_f32 v80, v86, v192
	v_cvt_pk_bf16_f32 v81, v88, v196
	v_cvt_pk_bf16_f32 v82, v90, v198
	v_cvt_pk_bf16_f32 v83, v92, v200
	v_cvt_pk_bf16_f32 v64, v68, v180
	v_cvt_pk_bf16_f32 v66, v74, v186
	v_mfma_f32_32x32x16_bf16 v[32:47], v[156:159], v[80:83], v[32:47]
	v_mfma_f32_32x32x16_bf16 v[16:31], v[160:163], v[80:83], v[16:31]
	s_waitcnt lgkmcnt(2)
	v_mfma_f32_32x32x16_bf16 v[32:47], v[144:147], v[64:67], v[32:47]
	s_waitcnt lgkmcnt(0)
	v_mfma_f32_32x32x16_bf16 v[16:31], v[10:13], v[64:67], v[16:31]

; __device__ __forceinline__ unsigned pk2(float lo, float hi) { f32x2 v = {lo, hi}; bf16x2_t b = __builtin_convertvector(v, bf16x2_t); return __builtin_bit_cast(unsigned, b); }
; __device__ __forceinline__ float hsum(float m) { auto rr = __builtin_amdgcn_permlane32_swap(__float_as_uint(m), __float_as_uint(m), false, false); return __uint_as_float(rr[0]) + __uint_as_float(rr[1]); }
; template <int TYPE, int ND0, int KSTR> __device__ __forceinline__ void tile(LAS unsigned char* lds, int buf, int t, int w_lo, int w_hi, int n, int qrel, int lane, int r32, int hi,
;         const bf16x8 (&qr)[ND0], float& m_run, float& l_run, f32x16& o0, f32x16& o1, f32x16& negm) {
;     ...
;     float ls = 0.f;
; #pragma unroll
;     for (int r = 0; r < 16; ++r) { p0[r] = __builtin_amdgcn_exp2f(p0[r]); p1[r] = __builtin_amdgcn_exp2f(p1[r]); ls += p0[r] + p1[r]; }
;     const float lrow = hsum(ls);
;     ...
; #pragma unroll
;     for (int ks = 0; ks < 4; ++ks) {
;         u32x4 pw;
;         if (ks < 2) { pw.x = pk2(p0[8 * ks], p0[8 * ks + 1]); pw.y = pk2(p0[8 * ks + 2], p0[8 * ks + 3]); pw.z = pk2(p0[8 * ks + 4], p0[8 * ks + 5]); pw.w = pk2(p0[8 * ks + 6], p0[8 * ks + 7]); }
;         else { const int k2 = ks - 2; pw.x = pk2(p1[8 * k2], p1[8 * k2 + 1]); pw.y = pk2(p1[8 * k2 + 2], p1[8 * k2 + 3]); pw.z = pk2(p1[8 * k2 + 4], p1[8 * k2 + 5]); pw.w = pk2(p1[8 * k2 + 6], p1[8 * k2 + 7]); }
;         const bf16x8 pb = __builtin_bit_cast(bf16x8, pw);
;         const bf16x8 va0 = __builtin_shufflevector(vf[ks][0], vf[ks][1], 0, 1, 2, 3, 4, 5, 6, 7), va1 = __builtin_shufflevector(vf[ks][2], vf[ks][3], 0, 1, 2, 3, 4, 5, 6, 7);
;         o0 = __builtin_amdgcn_mfma_f32_32x32x16_bf16(va0, pb, o0, 0, 0, 0);
;         o1 = __builtin_amdgcn_mfma_f32_32x32x16_bf16(va1, pb, o1, 0, 0, 0);
;     }
.LBB0_624:
	s_nop 7
	v_exp_f32_e32 v80, v80
	v_exp_f32_e32 v14, v64
	v_exp_f32_e32 v0, v81
	v_exp_f32_e32 v174, v65
	v_exp_f32_e32 v82, v82
	v_add_f32_e32 v175, v14, v80
	v_exp_f32_e32 v176, v67
	v_pk_add_f32 v[64:65], v[174:175], v[0:1]
	v_exp_f32_e32 v84, v84
	v_pk_add_f32 v[188:189], v[64:65], v[64:65] op_sel_hi:[0,1]
	v_exp_f32_e32 v64, v66
	v_exp_f32_e32 v188, v83
	v_exp_f32_e32 v178, v69
	v_exp_f32_e32 v172, v86
	v_add_f32_e32 v177, v64, v82
	v_pk_add_f32 v[66:67], v[176:177], v[188:189]
	v_exp_f32_e32 v70, v70
	v_pk_add_f32 v[190:191], v[66:67], v[66:67] op_sel_hi:[0,1]
	v_exp_f32_e32 v66, v68
	v_exp_f32_e32 v190, v85
	v_exp_f32_e32 v182, v71
	v_add_f32_e32 v183, v70, v172
	v_add_f32_e32 v179, v66, v84
	v_pk_add_f32 v[68:69], v[178:179], v[190:191]
	v_exp_f32_e32 v86, v88
	v_pk_add_f32 v[194:195], v[68:69], v[68:69] op_sel_hi:[0,1]
	v_exp_f32_e32 v194, v87
	v_cvt_pk_bf16_f32 v96, v80, v0
	v_cvt_pk_bf16_f32 v97, v82, v188
	v_cvt_pk_bf16_f32 v98, v84, v190
	v_cvt_pk_bf16_f32 v99, v172, v194
	v_cvt_pk_bf16_f32 v100, v14, v174
	v_cvt_pk_bf16_f32 v101, v64, v176
	v_cvt_pk_bf16_f32 v102, v66, v178
	v_cvt_pk_bf16_f32 v103, v70, v182
	v_mfma_f32_32x32x16_bf16 v[32:47], v[164:167], v[96:99], v[32:47]
	s_waitcnt lgkmcnt(12)
	v_mfma_f32_32x32x16_bf16 v[16:31], v[168:171], v[96:99], v[16:31]
	s_waitcnt lgkmcnt(6)
	v_mfma_f32_32x32x16_bf16 v[32:47], v[148:151], v[100:103], v[32:47]
	s_waitcnt lgkmcnt(4)
	v_mfma_f32_32x32x16_bf16 v[16:31], v[152:155], v[100:103], v[16:31]
	v_exp_f32_e32 v180, v73
	v_exp_f32_e32 v88, v90
	v_exp_f32_e32 v184, v75
	v_pk_add_f32 v[68:69], v[182:183], v[194:195]
	v_exp_f32_e32 v90, v92
	v_pk_add_f32 v[192:193], v[68:69], v[68:69] op_sel_hi:[0,1]
	v_exp_f32_e32 v68, v72
	v_exp_f32_e32 v192, v89
	v_exp_f32_e32 v186, v77
	v_exp_f32_e32 v92, v94
	v_add_f32_e32 v181, v68, v86
	v_pk_add_f32 v[72:73], v[180:181], v[192:193]
	s_mov_b32 s2, 0x53800000
	v_pk_add_f32 v[196:197], v[72:73], v[72:73] op_sel_hi:[0,1]
	v_exp_f32_e32 v72, v74
	v_exp_f32_e32 v196, v91
	v_add_f32_e32 v185, v72, v88
	v_pk_add_f32 v[74:75], v[184:185], v[196:197]
	s_nop 0
	v_pk_add_f32 v[198:199], v[74:75], v[74:75] op_sel_hi:[0,1]
	v_exp_f32_e32 v74, v76
	v_exp_f32_e32 v198, v93
	v_add_f32_e32 v187, v74, v90
	v_pk_add_f32 v[76:77], v[186:187], v[198:199]
	s_nop 0
	v_pk_add_f32 v[200:201], v[76:77], v[76:77] op_sel_hi:[0,1]
	v_exp_f32_e32 v76, v78
	v_exp_f32_e32 v200, v95
	v_exp_f32_e32 v78, v79
	v_add_f32_e32 v79, v76, v92
	v_pk_add_f32 v[94:95], v[78:79], v[200:201]
	s_nop 0
	v_pk_add_f32 v[94:95], v[94:95], v[94:95] op_sel:[0,1] op_sel_hi:[1,0]
	s_nop 0
	v_mov_b32_e32 v15, v94
	v_mov_b32_e32 v65, v94
	s_nop 1
	v_permlane32_swap_b32_e32 v15, v65
	v_add_f32_e32 v15, v15, v65
	v_cmp_lt_f32_e32 vcc, s2, v15
	s_cbranch_vccz .LBB0_626
; __device__ __forceinline__ float hmax(float m) { auto rr = __builtin_amdgcn_permlane32_swap(__float_as_uint(m), __float_as_uint(m), false, false); return fmaxf(__uint_as_float(rr[0]), __uint_as_float(rr[1])); }
; template <int TYPE, int ND0, int KSTR> __device__ __forceinline__ void tile(LAS unsigned char* lds, int buf, int t, int w_lo, int w_hi, int n, int qrel, int lane, int r32, int hi,
;         const bf16x8 (&qr)[ND0], float& m_run, float& l_run, f32x16& o0, f32x16& o1, f32x16& negm) {
;     ...
;     if (__builtin_amdgcn_ballot_w64(lrow > 1099511627776.0f) != 0ull) {
;         float pm = fmaxf(p0[0], p1[0]);
; #pragma unroll
;         for (int r = 1; r < 16; ++r) pm = fmaxf(pm, fmaxf(p0[r], p1[r]));
;         pm = hmax(pm);
;         const float dl = (lrow > 1099511627776.0f) ? __builtin_amdgcn_logf(pm) : 0.f;
;         const float sc = __builtin_amdgcn_exp2f(-dl);
;         m_run += dl; l_run *= sc; ls *= sc;
; #pragma unroll
;         for (int r = 0; r < 16; ++r) { p0[r] *= sc; p1[r] *= sc; o0[r] *= sc; o1[r] *= sc; negm[r] = -m_run; }
;     }
	v_max_f32_e32 v15, v174, v174
	v_max_f32_e32 v48, v0, v0
	v_max_f32_e32 v15, v48, v15
	v_max_f32_e32 v48, v64, v64
	v_max_f32_e32 v49, v82, v82
	v_max_f32_e32 v48, v49, v48
	v_max_f32_e32 v49, v176, v176
	v_max_f32_e32 v50, v188, v188
	v_max3_f32 v15, v80, v14, v15
	v_max_f32_e32 v49, v50, v49
	v_max3_f32 v15, v15, v48, v49
	v_max_f32_e32 v48, v66, v66
	v_max_f32_e32 v49, v84, v84
	v_max_f32_e32 v48, v49, v48
	v_max_f32_e32 v49, v178, v178
	v_max_f32_e32 v50, v190, v190
	v_max_f32_e32 v49, v50, v49
	v_max3_f32 v15, v15, v48, v49
	v_max_f32_e32 v48, v70, v70
	v_max_f32_e32 v49, v172, v172
	v_max_f32_e32 v48, v49, v48
	v_max_f32_e32 v49, v182, v182
	v_max_f32_e32 v50, v194, v194
	v_max_f32_e32 v49, v50, v49
	v_max3_f32 v15, v15, v48, v49
	v_max_f32_e32 v48, v68, v68
	v_max_f32_e32 v49, v86, v86
	v_max_f32_e32 v48, v49, v48
	v_max_f32_e32 v49, v180, v180
	v_max_f32_e32 v50, v192, v192
	v_max_f32_e32 v49, v50, v49
	v_max3_f32 v15, v15, v48, v49
	v_max_f32_e32 v48, v72, v72
	v_max_f32_e32 v49, v88, v88
	v_max_f32_e32 v48, v49, v48
	v_max_f32_e32 v49, v184, v184
	v_max_f32_e32 v50, v196, v196
	v_max_f32_e32 v49, v50, v49
	v_max3_f32 v15, v15, v48, v49
	v_max_f32_e32 v48, v74, v74
	v_max_f32_e32 v49, v90, v90
	v_max_f32_e32 v48, v49, v48
	v_max_f32_e32 v49, v186, v186
	v_max_f32_e32 v50, v198, v198
	v_max_f32_e32 v49, v50, v49
	v_max3_f32 v15, v15, v48, v49
	v_max_f32_e32 v48, v76, v76
	v_max_f32_e32 v49, v92, v92
	v_max_f32_e32 v48, v49, v48
	v_max_f32_e32 v49, v78, v78
	v_max_f32_e32 v50, v200, v200
	v_max_f32_e32 v49, v50, v49
	v_max3_f32 v15, v15, v48, v49
	v_mov_b32_e32 v48, v15
	s_nop 1
	v_permlane32_swap_b32_e32 v15, v48
	v_max_f32_e32 v48, v48, v48
	v_max_f32_e32 v15, v15, v15
	v_max_f32_e32 v15, v15, v48
	v_log_f32_e32 v15, v15
	v_mov_b32_e32 v223, v94
	v_mov_b32_e32 v93, v200
	v_mov_b32_e32 v91, v198
	v_cndmask_b32_e32 v15, 0, v15, vcc
	v_exp_f32_e64 v94, -v15
	v_add_f32_e32 v225, v225, v15
	v_mov_b32_e32 v89, v196
	v_mov_b32_e32 v87, v192
	v_mov_b32_e32 v173, v194
	v_mov_b32_e32 v85, v190
	v_mov_b32_e32 v83, v188
	v_mov_b32_e32 v81, v0
	v_mov_b32_e32 v77, v78
	v_mov_b32_e32 v75, v186
	v_mov_b32_e32 v73, v184
	v_mov_b32_e32 v69, v180
	v_mov_b32_e32 v71, v182
	v_mov_b32_e32 v67, v178
	v_mov_b32_e32 v65, v176
	v_mov_b32_e32 v15, v174
	v_xor_b32_e32 v48, 0x80000000, v225
	v_pk_mul_f32 v[92:93], v[92:93], v[94:95] op_sel_hi:[1,0]
	v_pk_mul_f32 v[90:91], v[90:91], v[94:95] op_sel_hi:[1,0]
	v_pk_mul_f32 v[88:89], v[88:89], v[94:95] op_sel_hi:[1,0]
	v_pk_mul_f32 v[86:87], v[86:87], v[94:95] op_sel_hi:[1,0]
	v_pk_mul_f32 v[172:173], v[172:173], v[94:95] op_sel_hi:[1,0]
	v_pk_mul_f32 v[84:85], v[84:85], v[94:95] op_sel_hi:[1,0]
	v_pk_mul_f32 v[82:83], v[82:83], v[94:95] op_sel_hi:[1,0]
	v_pk_mul_f32 v[80:81], v[80:81], v[94:95] op_sel_hi:[1,0]
	v_pk_mul_f32 v[76:77], v[76:77], v[94:95] op_sel_hi:[1,0]
	v_pk_mul_f32 v[74:75], v[74:75], v[94:95] op_sel_hi:[1,0]
	v_pk_mul_f32 v[72:73], v[72:73], v[94:95] op_sel_hi:[1,0]
	v_pk_mul_f32 v[68:69], v[68:69], v[94:95] op_sel_hi:[1,0]
	v_pk_mul_f32 v[70:71], v[70:71], v[94:95] op_sel_hi:[1,0]
	v_pk_mul_f32 v[66:67], v[66:67], v[94:95] op_sel_hi:[1,0]
	v_pk_mul_f32 v[64:65], v[64:65], v[94:95] op_sel_hi:[1,0]
	v_pk_mul_f32 v[14:15], v[14:15], v[94:95] op_sel_hi:[1,0]
	v_pk_mul_f32 v[222:223], v[222:223], v[94:95] op_sel_hi:[1,0]
	v_pk_mul_f32 v[46:47], v[46:47], v[94:95] op_sel_hi:[1,0]
	v_pk_mul_f32 v[44:45], v[44:45], v[94:95] op_sel_hi:[1,0]
	v_pk_mul_f32 v[42:43], v[42:43], v[94:95] op_sel_hi:[1,0]
	v_pk_mul_f32 v[40:41], v[40:41], v[94:95] op_sel_hi:[1,0]
	v_pk_mul_f32 v[38:39], v[38:39], v[94:95] op_sel_hi:[1,0]
	v_pk_mul_f32 v[36:37], v[36:37], v[94:95] op_sel_hi:[1,0]
	v_pk_mul_f32 v[34:35], v[34:35], v[94:95] op_sel_hi:[1,0]
	v_pk_mul_f32 v[32:33], v[32:33], v[94:95] op_sel_hi:[1,0]
	v_pk_mul_f32 v[30:31], v[30:31], v[94:95] op_sel_hi:[1,0]
	v_pk_mul_f32 v[28:29], v[28:29], v[94:95] op_sel_hi:[1,0]
	v_pk_mul_f32 v[26:27], v[26:27], v[94:95] op_sel_hi:[1,0]
	v_pk_mul_f32 v[24:25], v[24:25], v[94:95] op_sel_hi:[1,0]
	v_pk_mul_f32 v[22:23], v[22:23], v[94:95] op_sel_hi:[1,0]
	v_pk_mul_f32 v[20:21], v[20:21], v[94:95] op_sel_hi:[1,0]
	v_pk_mul_f32 v[18:19], v[18:19], v[94:95] op_sel_hi:[1,0]
	v_pk_mul_f32 v[16:17], v[16:17], v[94:95] op_sel_hi:[1,0]
	v_mov_b32_e32 v49, v48
	v_mov_b32_e32 v50, v48
	v_mov_b32_e32 v51, v48
	v_mov_b32_e32 v52, v48
	v_mov_b32_e32 v53, v48
	v_mov_b32_e32 v54, v48
	v_mov_b32_e32 v55, v48
	v_mov_b32_e32 v56, v48
	v_mov_b32_e32 v57, v48
	v_mov_b32_e32 v58, v48
	v_mov_b32_e32 v59, v48
	v_mov_b32_e32 v60, v48
	v_mov_b32_e32 v61, v48
	v_mov_b32_e32 v62, v48
	v_mov_b32_e32 v63, v48
	v_mov_b32_e32 v174, v15
	v_mov_b32_e32 v176, v65
	v_mov_b32_e32 v178, v67
	v_mov_b32_e32 v182, v71
	v_mov_b32_e32 v180, v69
	v_mov_b32_e32 v184, v73
	v_mov_b32_e32 v186, v75
	v_mov_b32_e32 v78, v77
	v_mov_b32_e32 v0, v81
	v_mov_b32_e32 v188, v83
	v_mov_b32_e32 v190, v85
	v_mov_b32_e32 v194, v173
	v_mov_b32_e32 v192, v87
	v_mov_b32_e32 v196, v89
	v_mov_b32_e32 v198, v91
	v_mov_b32_e32 v200, v93
	v_mov_b32_e32 v94, v223

; __device__ __forceinline__ unsigned pk2(float lo, float hi) { f32x2 v = {lo, hi}; bf16x2_t b = __builtin_convertvector(v, bf16x2_t); return __builtin_bit_cast(unsigned, b); }
; __device__ __forceinline__ float hsum(float m) { auto rr = __builtin_amdgcn_permlane32_swap(__float_as_uint(m), __float_as_uint(m), false, false); return __uint_as_float(rr[0]) + __uint_as_float(rr[1]); }
; template <int TYPE, int ND0, int KSTR> __device__ __forceinline__ void tile(LAS unsigned char* lds, int buf, int t, int w_lo, int w_hi, int n, int qrel, int lane, int r32, int hi,
;         const bf16x8 (&qr)[ND0], float& m_run, float& l_run, f32x16& o0, f32x16& o1, f32x16& negm) {
;     ...
;     float ls = 0.f;
; #pragma unroll
;     for (int r = 0; r < 16; ++r) { p0[r] = __builtin_amdgcn_exp2f(p0[r]); p1[r] = __builtin_amdgcn_exp2f(p1[r]); ls += p0[r] + p1[r]; }
;     const float lrow = hsum(ls);
;     ...
; #pragma unroll
;     for (int ks = 0; ks < 4; ++ks) {
;         u32x4 pw;
;         if (ks < 2) { pw.x = pk2(p0[8 * ks], p0[8 * ks + 1]); pw.y = pk2(p0[8 * ks + 2], p0[8 * ks + 3]); pw.z = pk2(p0[8 * ks + 4], p0[8 * ks + 5]); pw.w = pk2(p0[8 * ks + 6], p0[8 * ks + 7]); }
;         else { const int k2 = ks - 2; pw.x = pk2(p1[8 * k2], p1[8 * k2 + 1]); pw.y = pk2(p1[8 * k2 + 2], p1[8 * k2 + 3]); pw.z = pk2(p1[8 * k2 + 4], p1[8 * k2 + 5]); pw.w = pk2(p1[8 * k2 + 6], p1[8 * k2 + 7]); }
;         const bf16x8 pb = __builtin_bit_cast(bf16x8, pw);
;         const bf16x8 va0 = __builtin_shufflevector(vf[ks][0], vf[ks][1], 0, 1, 2, 3, 4, 5, 6, 7), va1 = __builtin_shufflevector(vf[ks][2], vf[ks][3], 0, 1, 2, 3, 4, 5, 6, 7);
;         o0 = __builtin_amdgcn_mfma_f32_32x32x16_bf16(va0, pb, o0, 0, 0, 0);
;         o1 = __builtin_amdgcn_mfma_f32_32x32x16_bf16(va1, pb, o1, 0, 0, 0);
;     }
.LBB0_662:
	v_exp_f32_e32 v74, v14
	v_exp_f32_e32 v14, v64
	v_exp_f32_e32 v0, v15
	v_exp_f32_e32 v188, v65
	v_exp_f32_e32 v78, v82
	v_add_f32_e32 v189, v14, v74
	v_exp_f32_e32 v190, v67
	v_pk_add_f32 v[64:65], v[188:189], v[0:1]
	v_exp_f32_e32 v82, v84
	v_pk_add_f32 v[202:203], v[64:65], v[64:65] op_sel_hi:[0,1]
	v_exp_f32_e32 v64, v66
	v_exp_f32_e32 v202, v83
	v_exp_f32_e32 v192, v69
	v_exp_f32_e32 v86, v86
	v_add_f32_e32 v191, v64, v78
	v_pk_add_f32 v[66:67], v[190:191], v[202:203]
	v_exp_f32_e32 v70, v70
	v_pk_add_f32 v[204:205], v[66:67], v[66:67] op_sel_hi:[0,1]
	v_exp_f32_e32 v66, v68
	v_exp_f32_e32 v204, v85
	v_exp_f32_e32 v198, v71
	v_add_f32_e32 v199, v70, v86
	v_add_f32_e32 v193, v66, v82
	v_pk_add_f32 v[68:69], v[192:193], v[204:205]
	v_exp_f32_e32 v84, v88
	v_pk_add_f32 v[220:221], v[68:69], v[68:69] op_sel_hi:[0,1]
	v_exp_f32_e32 v220, v87
	v_cvt_pk_bf16_f32 v208, v74, v0
	v_cvt_pk_bf16_f32 v209, v78, v202
	v_cvt_pk_bf16_f32 v210, v82, v204
	v_cvt_pk_bf16_f32 v211, v86, v220
	v_cvt_pk_bf16_f32 v100, v14, v188
	v_cvt_pk_bf16_f32 v101, v64, v190
	v_cvt_pk_bf16_f32 v102, v66, v192
	v_cvt_pk_bf16_f32 v103, v70, v198
	v_mfma_f32_32x32x16_bf16 v[32:47], v[168:171], v[208:211], v[32:47]
	v_mfma_f32_32x32x16_bf16 v[16:31], v[164:167], v[208:211], v[16:31]
	v_mfma_f32_32x32x16_bf16 v[32:47], v[152:155], v[100:103], v[32:47]
	v_mfma_f32_32x32x16_bf16 v[16:31], v[148:151], v[100:103], v[16:31]
	v_exp_f32_e32 v196, v73
	v_exp_f32_e32 v88, v90
	v_exp_f32_e32 v76, v76
	v_pk_add_f32 v[68:69], v[198:199], v[220:221]
	v_exp_f32_e32 v200, v77
	v_pk_add_f32 v[206:207], v[68:69], v[68:69] op_sel_hi:[0,1]
	v_exp_f32_e32 v68, v72
	v_exp_f32_e32 v206, v89
	v_exp_f32_e32 v80, v80
	s_mov_b32 s22, 0x53800000
	v_add_f32_e32 v197, v68, v84
	v_pk_add_f32 v[72:73], v[196:197], v[206:207]
	s_nop 0
	v_pk_add_f32 v[222:223], v[72:73], v[72:73] op_sel_hi:[0,1]
	v_exp_f32_e32 v72, v194
	v_exp_f32_e32 v222, v91
	v_exp_f32_e32 v194, v195
	v_add_f32_e32 v195, v72, v88
	v_pk_add_f32 v[90:91], v[194:195], v[222:223]
	s_nop 0
	v_pk_add_f32 v[224:225], v[90:91], v[90:91] op_sel_hi:[0,1]
	v_exp_f32_e32 v90, v92
	v_exp_f32_e32 v224, v93
	v_add_f32_e32 v201, v76, v90
	v_pk_add_f32 v[92:93], v[200:201], v[224:225]
	s_nop 0
	v_pk_add_f32 v[226:227], v[92:93], v[92:93] op_sel_hi:[0,1]
	v_exp_f32_e32 v92, v94
	v_exp_f32_e32 v226, v95
	v_exp_f32_e32 v94, v81
	v_add_f32_e32 v95, v80, v92
	v_pk_add_f32 v[208:209], v[94:95], v[226:227]
	s_nop 0
	v_pk_add_f32 v[228:229], v[208:209], v[208:209] op_sel:[0,1] op_sel_hi:[1,0]
	s_nop 0
	v_mov_b32_e32 v15, v228
	v_mov_b32_e32 v65, v228
	s_nop 1
	v_permlane32_swap_b32_e32 v15, v65
	v_add_f32_e32 v15, v15, v65
	v_cmp_lt_f32_e32 vcc, s22, v15
	s_cbranch_vccz .LBB0_664
; __device__ __forceinline__ unsigned pk2(float lo, float hi) { f32x2 v = {lo, hi}; bf16x2_t b = __builtin_convertvector(v, bf16x2_t); return __builtin_bit_cast(unsigned, b); }
; __device__ __forceinline__ float hmax(float m) { auto rr = __builtin_amdgcn_permlane32_swap(__float_as_uint(m), __float_as_uint(m), false, false); return fmaxf(__uint_as_float(rr[0]), __uint_as_float(rr[1])); }
; template <int TYPE, int ND0, int KSTR> __device__ __forceinline__ void tile(LAS unsigned char* lds, int buf, int t, int w_lo, int w_hi, int n, int qrel, int lane, int r32, int hi,
;         const bf16x8 (&qr)[ND0], float& m_run, float& l_run, f32x16& o0, f32x16& o1, f32x16& negm) {
;     ...
;     if (__builtin_amdgcn_ballot_w64(lrow > 1099511627776.0f) != 0ull) {
;         float pm = fmaxf(p0[0], p1[0]);
; #pragma unroll
;         for (int r = 1; r < 16; ++r) pm = fmaxf(pm, fmaxf(p0[r], p1[r]));
;         pm = hmax(pm);
;         const float dl = (lrow > 1099511627776.0f) ? __builtin_amdgcn_logf(pm) : 0.f;
;         const float sc = __builtin_amdgcn_exp2f(-dl);
;         m_run += dl; l_run *= sc; ls *= sc;
; #pragma unroll
;         for (int r = 0; r < 16; ++r) { p0[r] *= sc; p1[r] *= sc; o0[r] *= sc; o1[r] *= sc; negm[r] = -m_run; }
;     }
;     l_run += ls;
; #pragma unroll
;     for (int ks = 0; ks < 4; ++ks) {
;         u32x4 pw;
;         if (ks < 2) { pw.x = pk2(p0[8 * ks], p0[8 * ks + 1]); pw.y = pk2(p0[8 * ks + 2], p0[8 * ks + 3]); pw.z = pk2(p0[8 * ks + 4], p0[8 * ks + 5]); pw.w = pk2(p0[8 * ks + 6], p0[8 * ks + 7]); }
;         else { const int k2 = ks - 2; pw.x = pk2(p1[8 * k2], p1[8 * k2 + 1]); pw.y = pk2(p1[8 * k2 + 2], p1[8 * k2 + 3]); pw.z = pk2(p1[8 * k2 + 4], p1[8 * k2 + 5]); pw.w = pk2(p1[8 * k2 + 6], p1[8 * k2 + 7]); }
;         const bf16x8 pb = __builtin_bit_cast(bf16x8, pw);
;         const bf16x8 va0 = __builtin_shufflevector(vf[ks][0], vf[ks][1], 0, 1, 2, 3, 4, 5, 6, 7), va1 = __builtin_shufflevector(vf[ks][2], vf[ks][3], 0, 1, 2, 3, 4, 5, 6, 7);
;         o0 = __builtin_amdgcn_mfma_f32_32x32x16_bf16(va0, pb, o0, 0, 0, 0);
;         o1 = __builtin_amdgcn_mfma_f32_32x32x16_bf16(va1, pb, o1, 0, 0, 0);
;     }
	v_max_f32_e32 v15, v188, v188
	v_max_f32_e32 v48, v0, v0
	v_max_f32_e32 v15, v48, v15
	v_max_f32_e32 v48, v64, v64
	v_max_f32_e32 v49, v78, v78
	v_max_f32_e32 v48, v49, v48
	v_max_f32_e32 v49, v190, v190
	v_max_f32_e32 v50, v202, v202
	v_max3_f32 v15, v74, v14, v15
	v_max_f32_e32 v49, v50, v49
	v_max3_f32 v15, v15, v48, v49
	v_max_f32_e32 v48, v66, v66
	v_max_f32_e32 v49, v82, v82
	v_max_f32_e32 v48, v49, v48
	v_max_f32_e32 v49, v192, v192
	v_max_f32_e32 v50, v204, v204
	v_max_f32_e32 v49, v50, v49
	v_max3_f32 v15, v15, v48, v49
	v_max_f32_e32 v48, v70, v70
	v_max_f32_e32 v49, v86, v86
	v_max_f32_e32 v48, v49, v48
	v_max_f32_e32 v49, v198, v198
	v_max_f32_e32 v50, v220, v220
	v_max_f32_e32 v49, v50, v49
	v_max3_f32 v15, v15, v48, v49
	v_max_f32_e32 v48, v68, v68
	v_max_f32_e32 v49, v84, v84
	v_max_f32_e32 v48, v49, v48
	v_max_f32_e32 v49, v196, v196
	v_max_f32_e32 v50, v206, v206
	v_max_f32_e32 v49, v50, v49
	v_max3_f32 v15, v15, v48, v49
	v_max_f32_e32 v48, v72, v72
	v_max_f32_e32 v49, v88, v88
	v_max_f32_e32 v48, v49, v48
	v_max_f32_e32 v49, v194, v194
	v_max_f32_e32 v50, v222, v222
	v_max_f32_e32 v49, v50, v49
	v_max3_f32 v15, v15, v48, v49
	v_max_f32_e32 v48, v76, v76
	v_max_f32_e32 v49, v90, v90
	v_max_f32_e32 v48, v49, v48
	v_max_f32_e32 v49, v200, v200
	v_max_f32_e32 v50, v224, v224
	v_max_f32_e32 v49, v50, v49
	v_max3_f32 v15, v15, v48, v49
	v_max_f32_e32 v48, v80, v80
	v_max_f32_e32 v49, v92, v92
	v_max_f32_e32 v48, v49, v48
	v_max_f32_e32 v49, v94, v94
	v_max_f32_e32 v50, v226, v226
	v_max_f32_e32 v49, v50, v49
	v_max3_f32 v15, v15, v48, v49
	v_mov_b32_e32 v48, v15
	s_nop 1
	v_permlane32_swap_b32_e32 v15, v48
	v_max_f32_e32 v48, v48, v48
	v_max_f32_e32 v15, v15, v15
	v_max_f32_e32 v15, v15, v48
	v_log_f32_e32 v15, v15
	v_mov_b32_e32 v179, v228
	v_mov_b32_e32 v93, v226
	v_mov_b32_e32 v91, v224
	v_cndmask_b32_e32 v15, 0, v15, vcc
	v_exp_f32_e64 v208, -v15
	v_add_f32_e32 v181, v181, v15
	v_mov_b32_e32 v89, v222
	v_mov_b32_e32 v85, v206
	v_mov_b32_e32 v87, v220
	v_mov_b32_e32 v83, v204
	v_mov_b32_e32 v79, v202
	v_mov_b32_e32 v75, v0
	v_mov_b32_e32 v81, v94
	v_mov_b32_e32 v77, v200
	v_mov_b32_e32 v73, v194
	v_mov_b32_e32 v69, v196
	v_mov_b32_e32 v71, v198
	v_mov_b32_e32 v67, v192
	v_mov_b32_e32 v65, v190
	v_mov_b32_e32 v15, v188
	v_xor_b32_e32 v48, 0x80000000, v181
	v_pk_mul_f32 v[92:93], v[92:93], v[208:209] op_sel_hi:[1,0]
	v_pk_mul_f32 v[90:91], v[90:91], v[208:209] op_sel_hi:[1,0]
	v_pk_mul_f32 v[88:89], v[88:89], v[208:209] op_sel_hi:[1,0]
	v_pk_mul_f32 v[84:85], v[84:85], v[208:209] op_sel_hi:[1,0]
	v_pk_mul_f32 v[86:87], v[86:87], v[208:209] op_sel_hi:[1,0]
	v_pk_mul_f32 v[82:83], v[82:83], v[208:209] op_sel_hi:[1,0]
	v_pk_mul_f32 v[78:79], v[78:79], v[208:209] op_sel_hi:[1,0]
	v_pk_mul_f32 v[74:75], v[74:75], v[208:209] op_sel_hi:[1,0]
	v_pk_mul_f32 v[80:81], v[80:81], v[208:209] op_sel_hi:[1,0]
	v_pk_mul_f32 v[76:77], v[76:77], v[208:209] op_sel_hi:[1,0]
	v_pk_mul_f32 v[72:73], v[72:73], v[208:209] op_sel_hi:[1,0]
	v_pk_mul_f32 v[68:69], v[68:69], v[208:209] op_sel_hi:[1,0]
	v_pk_mul_f32 v[70:71], v[70:71], v[208:209] op_sel_hi:[1,0]
	v_pk_mul_f32 v[66:67], v[66:67], v[208:209] op_sel_hi:[1,0]
	v_pk_mul_f32 v[64:65], v[64:65], v[208:209] op_sel_hi:[1,0]
	v_pk_mul_f32 v[14:15], v[14:15], v[208:209] op_sel_hi:[1,0]
	v_pk_mul_f32 v[178:179], v[178:179], v[208:209] op_sel_hi:[1,0]
	v_pk_mul_f32 v[46:47], v[46:47], v[208:209] op_sel_hi:[1,0]
	v_pk_mul_f32 v[44:45], v[44:45], v[208:209] op_sel_hi:[1,0]
	v_pk_mul_f32 v[42:43], v[42:43], v[208:209] op_sel_hi:[1,0]
	v_pk_mul_f32 v[40:41], v[40:41], v[208:209] op_sel_hi:[1,0]
	v_pk_mul_f32 v[38:39], v[38:39], v[208:209] op_sel_hi:[1,0]
	v_pk_mul_f32 v[36:37], v[36:37], v[208:209] op_sel_hi:[1,0]
	v_pk_mul_f32 v[34:35], v[34:35], v[208:209] op_sel_hi:[1,0]
	v_pk_mul_f32 v[32:33], v[32:33], v[208:209] op_sel_hi:[1,0]
	v_pk_mul_f32 v[30:31], v[30:31], v[208:209] op_sel_hi:[1,0]
	v_pk_mul_f32 v[28:29], v[28:29], v[208:209] op_sel_hi:[1,0]
	v_pk_mul_f32 v[26:27], v[26:27], v[208:209] op_sel_hi:[1,0]
	v_pk_mul_f32 v[24:25], v[24:25], v[208:209] op_sel_hi:[1,0]
	v_pk_mul_f32 v[22:23], v[22:23], v[208:209] op_sel_hi:[1,0]
	v_pk_mul_f32 v[20:21], v[20:21], v[208:209] op_sel_hi:[1,0]
	v_pk_mul_f32 v[18:19], v[18:19], v[208:209] op_sel_hi:[1,0]
	v_pk_mul_f32 v[16:17], v[16:17], v[208:209] op_sel_hi:[1,0]
	v_mov_b32_e32 v49, v48
	v_mov_b32_e32 v50, v48
	v_mov_b32_e32 v51, v48
	v_mov_b32_e32 v52, v48
	v_mov_b32_e32 v53, v48
	v_mov_b32_e32 v54, v48
	v_mov_b32_e32 v55, v48
	v_mov_b32_e32 v56, v48
	v_mov_b32_e32 v57, v48
	v_mov_b32_e32 v58, v48
	v_mov_b32_e32 v59, v48
	v_mov_b32_e32 v60, v48
	v_mov_b32_e32 v61, v48
	v_mov_b32_e32 v62, v48
	v_mov_b32_e32 v63, v48
	v_mov_b32_e32 v188, v15
	v_mov_b32_e32 v190, v65
	v_mov_b32_e32 v192, v67
	v_mov_b32_e32 v198, v71
	v_mov_b32_e32 v196, v69
	v_mov_b32_e32 v194, v73
	v_mov_b32_e32 v200, v77
	v_mov_b32_e32 v94, v81
	v_mov_b32_e32 v0, v75
	v_mov_b32_e32 v202, v79
	v_mov_b32_e32 v204, v83
	v_mov_b32_e32 v220, v87
	v_mov_b32_e32 v206, v85
	v_mov_b32_e32 v222, v89
	v_mov_b32_e32 v224, v91
	v_mov_b32_e32 v226, v93
	v_mov_b32_e32 v228, v179
.LBB0_664:
	v_cvt_pk_bf16_f32 v82, v84, v206
	v_cvt_pk_bf16_f32 v83, v88, v222
	v_cvt_pk_bf16_f32 v84, v90, v224
	v_cvt_pk_bf16_f32 v85, v92, v226
	v_cvt_pk_bf16_f32 v65, v72, v194
	v_cvt_pk_bf16_f32 v67, v80, v94
	v_cvt_pk_bf16_f32 v64, v68, v196
	v_cvt_pk_bf16_f32 v66, v76, v200
	v_add_f32_e32 v178, v178, v228
	v_mfma_f32_32x32x16_bf16 v[32:47], v[156:159], v[82:85], v[32:47]
	v_mfma_f32_32x32x16_bf16 v[16:31], v[160:163], v[82:85], v[16:31]
	v_mfma_f32_32x32x16_bf16 v[32:47], v[144:147], v[64:67], v[32:47]
	v_mfma_f32_32x32x16_bf16 v[16:31], v[10:13], v[64:67], v[16:31]

; __device__ __forceinline__ unsigned pk2(float lo, float hi) { f32x2 v = {lo, hi}; bf16x2_t b = __builtin_convertvector(v, bf16x2_t); return __builtin_bit_cast(unsigned, b); }
; __device__ __forceinline__ float hsum(float m) { auto rr = __builtin_amdgcn_permlane32_swap(__float_as_uint(m), __float_as_uint(m), false, false); return __uint_as_float(rr[0]) + __uint_as_float(rr[1]); }
; template <int TYPE, int ND0, int KSTR> __device__ __forceinline__ void tile(LAS unsigned char* lds, int buf, int t, int w_lo, int w_hi, int n, int qrel, int lane, int r32, int hi,
;         const bf16x8 (&qr)[ND0], float& m_run, float& l_run, f32x16& o0, f32x16& o1, f32x16& negm) {
;     ...
;     float ls = 0.f;
; #pragma unroll
;     for (int r = 0; r < 16; ++r) { p0[r] = __builtin_amdgcn_exp2f(p0[r]); p1[r] = __builtin_amdgcn_exp2f(p1[r]); ls += p0[r] + p1[r]; }
;     const float lrow = hsum(ls);
;     ...
; #pragma unroll
;     for (int ks = 0; ks < 4; ++ks) {
;         u32x4 pw;
;         if (ks < 2) { pw.x = pk2(p0[8 * ks], p0[8 * ks + 1]); pw.y = pk2(p0[8 * ks + 2], p0[8 * ks + 3]); pw.z = pk2(p0[8 * ks + 4], p0[8 * ks + 5]); pw.w = pk2(p0[8 * ks + 6], p0[8 * ks + 7]); }
;         else { const int k2 = ks - 2; pw.x = pk2(p1[8 * k2], p1[8 * k2 + 1]); pw.y = pk2(p1[8 * k2 + 2], p1[8 * k2 + 3]); pw.z = pk2(p1[8 * k2 + 4], p1[8 * k2 + 5]); pw.w = pk2(p1[8 * k2 + 6], p1[8 * k2 + 7]); }
;         const bf16x8 pb = __builtin_bit_cast(bf16x8, pw);
;         const bf16x8 va0 = __builtin_shufflevector(vf[ks][0], vf[ks][1], 0, 1, 2, 3, 4, 5, 6, 7), va1 = __builtin_shufflevector(vf[ks][2], vf[ks][3], 0, 1, 2, 3, 4, 5, 6, 7);
;         o0 = __builtin_amdgcn_mfma_f32_32x32x16_bf16(va0, pb, o0, 0, 0, 0);
;         o1 = __builtin_amdgcn_mfma_f32_32x32x16_bf16(va1, pb, o1, 0, 0, 0);
;     }
.LBB0_670:
	v_exp_f32_e32 v74, v14
	v_exp_f32_e32 v14, v64
	v_exp_f32_e32 v0, v15
	v_exp_f32_e32 v94, v65
	v_exp_f32_e32 v78, v82
	v_add_f32_e32 v95, v14, v74
	v_exp_f32_e32 v188, v67
	v_pk_add_f32 v[64:65], v[94:95], v[0:1]
	v_exp_f32_e32 v82, v84
	v_pk_add_f32 v[200:201], v[64:65], v[64:65] op_sel_hi:[0,1]
	v_exp_f32_e32 v64, v66
	v_exp_f32_e32 v200, v83
	v_exp_f32_e32 v190, v69
	v_exp_f32_e32 v86, v86
	v_add_f32_e32 v189, v64, v78
	v_pk_add_f32 v[66:67], v[188:189], v[200:201]
	v_exp_f32_e32 v70, v70
	v_pk_add_f32 v[204:205], v[66:67], v[66:67] op_sel_hi:[0,1]
	v_exp_f32_e32 v66, v68
	v_exp_f32_e32 v204, v85
	v_exp_f32_e32 v194, v71
	v_add_f32_e32 v195, v70, v86
	v_add_f32_e32 v191, v66, v82
	v_pk_add_f32 v[68:69], v[190:191], v[204:205]
	v_exp_f32_e32 v84, v88
	v_pk_add_f32 v[220:221], v[68:69], v[68:69] op_sel_hi:[0,1]
	v_exp_f32_e32 v220, v87
	v_cvt_pk_bf16_f32 v208, v74, v0
	v_cvt_pk_bf16_f32 v209, v78, v200
	v_cvt_pk_bf16_f32 v210, v82, v204
	v_cvt_pk_bf16_f32 v211, v86, v220
	v_cvt_pk_bf16_f32 v100, v14, v94
	v_cvt_pk_bf16_f32 v101, v64, v188
	v_cvt_pk_bf16_f32 v102, v66, v190
	v_cvt_pk_bf16_f32 v103, v70, v194
	v_mfma_f32_32x32x16_bf16 v[32:47], v[168:171], v[208:211], v[32:47]
	v_mfma_f32_32x32x16_bf16 v[16:31], v[164:167], v[208:211], v[16:31]
	v_mfma_f32_32x32x16_bf16 v[32:47], v[152:155], v[100:103], v[32:47]
	v_mfma_f32_32x32x16_bf16 v[16:31], v[148:151], v[100:103], v[16:31]
	v_exp_f32_e32 v192, v73
	v_exp_f32_e32 v88, v90
	v_exp_f32_e32 v76, v76
	v_pk_add_f32 v[68:69], v[194:195], v[220:221]
	v_exp_f32_e32 v198, v77
	v_pk_add_f32 v[206:207], v[68:69], v[68:69] op_sel_hi:[0,1]
	v_exp_f32_e32 v68, v72
	v_exp_f32_e32 v206, v89
	v_exp_f32_e32 v80, v80
	s_mov_b32 s2, 0x53800000
	v_add_f32_e32 v193, v68, v84
	v_pk_add_f32 v[72:73], v[192:193], v[206:207]
	s_nop 0
	v_pk_add_f32 v[222:223], v[72:73], v[72:73] op_sel_hi:[0,1]
	v_exp_f32_e32 v72, v196
	v_exp_f32_e32 v222, v91
	v_exp_f32_e32 v196, v197
	v_add_f32_e32 v197, v72, v88
	v_pk_add_f32 v[90:91], v[196:197], v[222:223]
	s_nop 0
	v_pk_add_f32 v[224:225], v[90:91], v[90:91] op_sel_hi:[0,1]
	v_exp_f32_e32 v90, v92
	v_exp_f32_e32 v224, v93
	v_add_f32_e32 v199, v76, v90
	v_pk_add_f32 v[92:93], v[198:199], v[224:225]
	s_nop 0
	v_pk_add_f32 v[226:227], v[92:93], v[92:93] op_sel_hi:[0,1]
	v_exp_f32_e32 v92, v202
	v_exp_f32_e32 v226, v203
	v_exp_f32_e32 v202, v81
	v_add_f32_e32 v203, v80, v92
	v_pk_add_f32 v[208:209], v[202:203], v[226:227]
	s_nop 0
	v_pk_add_f32 v[228:229], v[208:209], v[208:209] op_sel:[0,1] op_sel_hi:[1,0]
	s_nop 0
	v_mov_b32_e32 v15, v228
	v_mov_b32_e32 v65, v228
	s_nop 1
	v_permlane32_swap_b32_e32 v15, v65
	v_add_f32_e32 v15, v15, v65
	v_cmp_lt_f32_e32 vcc, s2, v15
	s_cbranch_vccz .LBB0_672
; __device__ __forceinline__ unsigned pk2(float lo, float hi) { f32x2 v = {lo, hi}; bf16x2_t b = __builtin_convertvector(v, bf16x2_t); return __builtin_bit_cast(unsigned, b); }
; __device__ __forceinline__ float hmax(float m) { auto rr = __builtin_amdgcn_permlane32_swap(__float_as_uint(m), __float_as_uint(m), false, false); return fmaxf(__uint_as_float(rr[0]), __uint_as_float(rr[1])); }
; template <int TYPE, int ND0, int KSTR> __device__ __forceinline__ void tile(LAS unsigned char* lds, int buf, int t, int w_lo, int w_hi, int n, int qrel, int lane, int r32, int hi,
;         const bf16x8 (&qr)[ND0], float& m_run, float& l_run, f32x16& o0, f32x16& o1, f32x16& negm) {
;     ...
;     if (__builtin_amdgcn_ballot_w64(lrow > 1099511627776.0f) != 0ull) {
;         float pm = fmaxf(p0[0], p1[0]);
; #pragma unroll
;         for (int r = 1; r < 16; ++r) pm = fmaxf(pm, fmaxf(p0[r], p1[r]));
;         pm = hmax(pm);
;         const float dl = (lrow > 1099511627776.0f) ? __builtin_amdgcn_logf(pm) : 0.f;
;         const float sc = __builtin_amdgcn_exp2f(-dl);
;         m_run += dl; l_run *= sc; ls *= sc;
; #pragma unroll
;         for (int r = 0; r < 16; ++r) { p0[r] *= sc; p1[r] *= sc; o0[r] *= sc; o1[r] *= sc; negm[r] = -m_run; }
;     }
;     l_run += ls;
; #pragma unroll
;     for (int ks = 0; ks < 4; ++ks) {
;         u32x4 pw;
;         if (ks < 2) { pw.x = pk2(p0[8 * ks], p0[8 * ks + 1]); pw.y = pk2(p0[8 * ks + 2], p0[8 * ks + 3]); pw.z = pk2(p0[8 * ks + 4], p0[8 * ks + 5]); pw.w = pk2(p0[8 * ks + 6], p0[8 * ks + 7]); }
;         else { const int k2 = ks - 2; pw.x = pk2(p1[8 * k2], p1[8 * k2 + 1]); pw.y = pk2(p1[8 * k2 + 2], p1[8 * k2 + 3]); pw.z = pk2(p1[8 * k2 + 4], p1[8 * k2 + 5]); pw.w = pk2(p1[8 * k2 + 6], p1[8 * k2 + 7]); }
;         const bf16x8 pb = __builtin_bit_cast(bf16x8, pw);
;         const bf16x8 va0 = __builtin_shufflevector(vf[ks][0], vf[ks][1], 0, 1, 2, 3, 4, 5, 6, 7), va1 = __builtin_shufflevector(vf[ks][2], vf[ks][3], 0, 1, 2, 3, 4, 5, 6, 7);
;         o0 = __builtin_amdgcn_mfma_f32_32x32x16_bf16(va0, pb, o0, 0, 0, 0);
;         o1 = __builtin_amdgcn_mfma_f32_32x32x16_bf16(va1, pb, o1, 0, 0, 0);
;     }
	v_max_f32_e32 v15, v94, v94
	v_max_f32_e32 v48, v0, v0
	v_max_f32_e32 v15, v48, v15
	v_max_f32_e32 v48, v64, v64
	v_max_f32_e32 v49, v78, v78
	v_max_f32_e32 v48, v49, v48
	v_max_f32_e32 v49, v188, v188
	v_max_f32_e32 v50, v200, v200
	v_max3_f32 v15, v74, v14, v15
	v_max_f32_e32 v49, v50, v49
	v_max3_f32 v15, v15, v48, v49
	v_max_f32_e32 v48, v66, v66
	v_max_f32_e32 v49, v82, v82
	v_max_f32_e32 v48, v49, v48
	v_max_f32_e32 v49, v190, v190
	v_max_f32_e32 v50, v204, v204
	v_max_f32_e32 v49, v50, v49
	v_max3_f32 v15, v15, v48, v49
	v_max_f32_e32 v48, v70, v70
	v_max_f32_e32 v49, v86, v86
	v_max_f32_e32 v48, v49, v48
	v_max_f32_e32 v49, v194, v194
	v_max_f32_e32 v50, v220, v220
	v_max_f32_e32 v49, v50, v49
	v_max3_f32 v15, v15, v48, v49
	v_max_f32_e32 v48, v68, v68
	v_max_f32_e32 v49, v84, v84
	v_max_f32_e32 v48, v49, v48
	v_max_f32_e32 v49, v192, v192
	v_max_f32_e32 v50, v206, v206
	v_max_f32_e32 v49, v50, v49
	v_max3_f32 v15, v15, v48, v49
	v_max_f32_e32 v48, v72, v72
	v_max_f32_e32 v49, v88, v88
	v_max_f32_e32 v48, v49, v48
	v_max_f32_e32 v49, v196, v196
	v_max_f32_e32 v50, v222, v222
	v_max_f32_e32 v49, v50, v49
	v_max3_f32 v15, v15, v48, v49
	v_max_f32_e32 v48, v76, v76
	v_max_f32_e32 v49, v90, v90
	v_max_f32_e32 v48, v49, v48
	v_max_f32_e32 v49, v198, v198
	v_max_f32_e32 v50, v224, v224
	v_max_f32_e32 v49, v50, v49
	v_max3_f32 v15, v15, v48, v49
	v_max_f32_e32 v48, v80, v80
	v_max_f32_e32 v49, v92, v92
	v_max_f32_e32 v48, v49, v48
	v_max_f32_e32 v49, v202, v202
	v_max_f32_e32 v50, v226, v226
	v_max_f32_e32 v49, v50, v49
	v_max3_f32 v15, v15, v48, v49
	v_mov_b32_e32 v48, v15
	s_nop 1
	v_permlane32_swap_b32_e32 v15, v48
	v_max_f32_e32 v48, v48, v48
	v_max_f32_e32 v15, v15, v15
	v_max_f32_e32 v15, v15, v48
	v_log_f32_e32 v15, v15
	v_mov_b32_e32 v179, v228
	v_mov_b32_e32 v93, v226
	v_mov_b32_e32 v91, v224
	v_cndmask_b32_e32 v15, 0, v15, vcc
	v_exp_f32_e64 v208, -v15
	v_add_f32_e32 v181, v181, v15
	v_mov_b32_e32 v89, v222
	v_mov_b32_e32 v85, v206
	v_mov_b32_e32 v87, v220
	v_mov_b32_e32 v83, v204
	v_mov_b32_e32 v79, v200
	v_mov_b32_e32 v75, v0
	v_mov_b32_e32 v81, v202
	v_mov_b32_e32 v77, v198
	v_mov_b32_e32 v73, v196
	v_mov_b32_e32 v69, v192
	v_mov_b32_e32 v71, v194
	v_mov_b32_e32 v67, v190
	v_mov_b32_e32 v65, v188
	v_mov_b32_e32 v15, v94
	v_xor_b32_e32 v48, 0x80000000, v181
	v_pk_mul_f32 v[92:93], v[92:93], v[208:209] op_sel_hi:[1,0]
	v_pk_mul_f32 v[90:91], v[90:91], v[208:209] op_sel_hi:[1,0]
	v_pk_mul_f32 v[88:89], v[88:89], v[208:209] op_sel_hi:[1,0]
	v_pk_mul_f32 v[84:85], v[84:85], v[208:209] op_sel_hi:[1,0]
	v_pk_mul_f32 v[86:87], v[86:87], v[208:209] op_sel_hi:[1,0]
	v_pk_mul_f32 v[82:83], v[82:83], v[208:209] op_sel_hi:[1,0]
	v_pk_mul_f32 v[78:79], v[78:79], v[208:209] op_sel_hi:[1,0]
	v_pk_mul_f32 v[74:75], v[74:75], v[208:209] op_sel_hi:[1,0]
	v_pk_mul_f32 v[80:81], v[80:81], v[208:209] op_sel_hi:[1,0]
	v_pk_mul_f32 v[76:77], v[76:77], v[208:209] op_sel_hi:[1,0]
	v_pk_mul_f32 v[72:73], v[72:73], v[208:209] op_sel_hi:[1,0]
	v_pk_mul_f32 v[68:69], v[68:69], v[208:209] op_sel_hi:[1,0]
	v_pk_mul_f32 v[70:71], v[70:71], v[208:209] op_sel_hi:[1,0]
	v_pk_mul_f32 v[66:67], v[66:67], v[208:209] op_sel_hi:[1,0]
	v_pk_mul_f32 v[64:65], v[64:65], v[208:209] op_sel_hi:[1,0]
	v_pk_mul_f32 v[14:15], v[14:15], v[208:209] op_sel_hi:[1,0]
	v_pk_mul_f32 v[178:179], v[178:179], v[208:209] op_sel_hi:[1,0]
	v_pk_mul_f32 v[46:47], v[46:47], v[208:209] op_sel_hi:[1,0]
	v_pk_mul_f32 v[44:45], v[44:45], v[208:209] op_sel_hi:[1,0]
	v_pk_mul_f32 v[42:43], v[42:43], v[208:209] op_sel_hi:[1,0]
	v_pk_mul_f32 v[40:41], v[40:41], v[208:209] op_sel_hi:[1,0]
	v_pk_mul_f32 v[38:39], v[38:39], v[208:209] op_sel_hi:[1,0]
	v_pk_mul_f32 v[36:37], v[36:37], v[208:209] op_sel_hi:[1,0]
	v_pk_mul_f32 v[34:35], v[34:35], v[208:209] op_sel_hi:[1,0]
	v_pk_mul_f32 v[32:33], v[32:33], v[208:209] op_sel_hi:[1,0]
	v_pk_mul_f32 v[30:31], v[30:31], v[208:209] op_sel_hi:[1,0]
	v_pk_mul_f32 v[28:29], v[28:29], v[208:209] op_sel_hi:[1,0]
	v_pk_mul_f32 v[26:27], v[26:27], v[208:209] op_sel_hi:[1,0]
	v_pk_mul_f32 v[24:25], v[24:25], v[208:209] op_sel_hi:[1,0]
	v_pk_mul_f32 v[22:23], v[22:23], v[208:209] op_sel_hi:[1,0]
	v_pk_mul_f32 v[20:21], v[20:21], v[208:209] op_sel_hi:[1,0]
	v_pk_mul_f32 v[18:19], v[18:19], v[208:209] op_sel_hi:[1,0]
	v_pk_mul_f32 v[16:17], v[16:17], v[208:209] op_sel_hi:[1,0]
	v_mov_b32_e32 v49, v48
	v_mov_b32_e32 v50, v48
	v_mov_b32_e32 v51, v48
	v_mov_b32_e32 v52, v48
	v_mov_b32_e32 v53, v48
	v_mov_b32_e32 v54, v48
	v_mov_b32_e32 v55, v48
	v_mov_b32_e32 v56, v48
	v_mov_b32_e32 v57, v48
	v_mov_b32_e32 v58, v48
	v_mov_b32_e32 v59, v48
	v_mov_b32_e32 v60, v48
	v_mov_b32_e32 v61, v48
	v_mov_b32_e32 v62, v48
	v_mov_b32_e32 v63, v48
	v_mov_b32_e32 v94, v15
	v_mov_b32_e32 v188, v65
	v_mov_b32_e32 v190, v67
	v_mov_b32_e32 v194, v71
	v_mov_b32_e32 v192, v69
	v_mov_b32_e32 v196, v73
	v_mov_b32_e32 v198, v77
	v_mov_b32_e32 v202, v81
	v_mov_b32_e32 v0, v75
	v_mov_b32_e32 v200, v79
	v_mov_b32_e32 v204, v83
	v_mov_b32_e32 v220, v87
	v_mov_b32_e32 v206, v85
	v_mov_b32_e32 v222, v89
	v_mov_b32_e32 v224, v91
	v_mov_b32_e32 v226, v93
	v_mov_b32_e32 v228, v179
.LBB0_672:
	v_cvt_pk_bf16_f32 v82, v84, v206
	v_cvt_pk_bf16_f32 v83, v88, v222
	v_cvt_pk_bf16_f32 v84, v90, v224
	v_cvt_pk_bf16_f32 v85, v92, v226
	v_cvt_pk_bf16_f32 v65, v72, v196
	v_cvt_pk_bf16_f32 v67, v80, v202
	v_cvt_pk_bf16_f32 v64, v68, v192
	v_cvt_pk_bf16_f32 v66, v76, v198
	v_add_f32_e32 v178, v178, v228
	v_mfma_f32_32x32x16_bf16 v[32:47], v[156:159], v[82:85], v[32:47]
	v_mfma_f32_32x32x16_bf16 v[16:31], v[160:163], v[82:85], v[16:31]
	v_mfma_f32_32x32x16_bf16 v[32:47], v[144:147], v[64:67], v[32:47]
	v_mfma_f32_32x32x16_bf16 v[16:31], v[10:13], v[64:67], v[16:31]

; __device__ __forceinline__ unsigned pk2(float lo, float hi) { f32x2 v = {lo, hi}; bf16x2_t b = __builtin_convertvector(v, bf16x2_t); return __builtin_bit_cast(unsigned, b); }
; __device__ __forceinline__ float hsum(float m) { auto rr = __builtin_amdgcn_permlane32_swap(__float_as_uint(m), __float_as_uint(m), false, false); return __uint_as_float(rr[0]) + __uint_as_float(rr[1]); }
; template <int TYPE, int ND0, int KSTR> __device__ __forceinline__ void tile(LAS unsigned char* lds, int buf, int t, int w_lo, int w_hi, int n, int qrel, int lane, int r32, int hi,
;         const bf16x8 (&qr)[ND0], float& m_run, float& l_run, f32x16& o0, f32x16& o1, f32x16& negm) {
;     ...
;     float ls = 0.f;
; #pragma unroll
;     for (int r = 0; r < 16; ++r) { p0[r] = __builtin_amdgcn_exp2f(p0[r]); p1[r] = __builtin_amdgcn_exp2f(p1[r]); ls += p0[r] + p1[r]; }
;     const float lrow = hsum(ls);
;     ...
; #pragma unroll
;     for (int ks = 0; ks < 4; ++ks) {
;         u32x4 pw;
;         if (ks < 2) { pw.x = pk2(p0[8 * ks], p0[8 * ks + 1]); pw.y = pk2(p0[8 * ks + 2], p0[8 * ks + 3]); pw.z = pk2(p0[8 * ks + 4], p0[8 * ks + 5]); pw.w = pk2(p0[8 * ks + 6], p0[8 * ks + 7]); }
;         else { const int k2 = ks - 2; pw.x = pk2(p1[8 * k2], p1[8 * k2 + 1]); pw.y = pk2(p1[8 * k2 + 2], p1[8 * k2 + 3]); pw.z = pk2(p1[8 * k2 + 4], p1[8 * k2 + 5]); pw.w = pk2(p1[8 * k2 + 6], p1[8 * k2 + 7]); }
;         const bf16x8 pb = __builtin_bit_cast(bf16x8, pw);
;         const bf16x8 va0 = __builtin_shufflevector(vf[ks][0], vf[ks][1], 0, 1, 2, 3, 4, 5, 6, 7), va1 = __builtin_shufflevector(vf[ks][2], vf[ks][3], 0, 1, 2, 3, 4, 5, 6, 7);
;         o0 = __builtin_amdgcn_mfma_f32_32x32x16_bf16(va0, pb, o0, 0, 0, 0);
;         o1 = __builtin_amdgcn_mfma_f32_32x32x16_bf16(va1, pb, o1, 0, 0, 0);
;     }
.LBB0_707:
	s_nop 0
	v_exp_f32_e32 v182, v64
	s_nop 8
	v_exp_f32_e32 v14, v80
	v_exp_f32_e32 v0, v65
	v_exp_f32_e32 v186, v81
	v_exp_f32_e32 v80, v66
	v_add_f32_e32 v187, v14, v182
	v_exp_f32_e32 v188, v83
	v_pk_add_f32 v[64:65], v[186:187], v[0:1]
	v_exp_f32_e32 v190, v85
	v_pk_add_f32 v[196:197], v[64:65], v[64:65] op_sel_hi:[0,1]
	v_exp_f32_e32 v64, v82
	v_exp_f32_e32 v196, v67
	v_exp_f32_e32 v82, v68
	v_exp_f32_e32 v184, v70
	v_add_f32_e32 v189, v64, v80
	v_pk_add_f32 v[66:67], v[188:189], v[196:197]
	v_exp_f32_e32 v70, v86
	v_pk_add_f32 v[198:199], v[66:67], v[66:67] op_sel_hi:[0,1]
	v_exp_f32_e32 v66, v84
	v_exp_f32_e32 v198, v69
	v_exp_f32_e32 v194, v87
	v_add_f32_e32 v195, v70, v184
	v_add_f32_e32 v191, v66, v82
	v_pk_add_f32 v[68:69], v[190:191], v[198:199]
	v_exp_f32_e32 v84, v72
	v_pk_add_f32 v[202:203], v[68:69], v[68:69] op_sel_hi:[0,1]
	v_exp_f32_e32 v202, v71
	v_cvt_pk_bf16_f32 v208, v182, v0
	v_cvt_pk_bf16_f32 v209, v80, v196
	v_cvt_pk_bf16_f32 v210, v82, v198
	v_cvt_pk_bf16_f32 v211, v184, v202
	v_cvt_pk_bf16_f32 v212, v14, v186
	v_cvt_pk_bf16_f32 v213, v64, v188
	v_cvt_pk_bf16_f32 v214, v66, v190
	v_cvt_pk_bf16_f32 v215, v70, v194
	v_mfma_f32_32x32x16_bf16 v[32:47], v[160:163], v[208:211], v[32:47]
	s_waitcnt lgkmcnt(12)
	v_mfma_f32_32x32x16_bf16 v[16:31], v[156:159], v[208:211], v[16:31]
	s_waitcnt lgkmcnt(6)
	v_mfma_f32_32x32x16_bf16 v[32:47], v[116:119], v[212:215], v[32:47]
	s_waitcnt lgkmcnt(4)
	v_mfma_f32_32x32x16_bf16 v[16:31], v[144:147], v[212:215], v[16:31]
	v_exp_f32_e32 v192, v89
	v_exp_f32_e32 v86, v74
	v_exp_f32_e32 v78, v78
	v_pk_add_f32 v[68:69], v[194:195], v[202:203]
	s_mov_b32 s5, 0x53800000
	v_pk_add_f32 v[200:201], v[68:69], v[68:69] op_sel_hi:[0,1]
	v_exp_f32_e32 v68, v88
	v_exp_f32_e32 v200, v73
	v_exp_f32_e32 v88, v76
	v_add_f32_e32 v193, v68, v84
	v_pk_add_f32 v[72:73], v[192:193], v[200:201]
	s_nop 0
	v_pk_add_f32 v[204:205], v[72:73], v[72:73] op_sel_hi:[0,1]
	v_exp_f32_e32 v72, v90
	v_exp_f32_e32 v204, v75
	v_exp_f32_e32 v90, v91
	v_add_f32_e32 v91, v72, v86
	v_pk_add_f32 v[74:75], v[90:91], v[204:205]
	s_nop 0
	v_pk_add_f32 v[206:207], v[74:75], v[74:75] op_sel_hi:[0,1]
	v_exp_f32_e32 v74, v92
	v_exp_f32_e32 v206, v77
	v_exp_f32_e32 v92, v93
	v_add_f32_e32 v93, v74, v88
	v_pk_add_f32 v[76:77], v[92:93], v[206:207]
	s_nop 0
	v_pk_add_f32 v[220:221], v[76:77], v[76:77] op_sel_hi:[0,1]
	v_exp_f32_e32 v76, v94
	v_exp_f32_e32 v220, v79
	v_exp_f32_e32 v94, v95
	v_add_f32_e32 v95, v76, v78
	v_pk_add_f32 v[208:209], v[94:95], v[220:221]
	s_nop 0
	v_pk_add_f32 v[222:223], v[208:209], v[208:209] op_sel:[0,1] op_sel_hi:[1,0]
	s_nop 0
	v_mov_b32_e32 v15, v222
	v_mov_b32_e32 v65, v222
	s_nop 1
	v_permlane32_swap_b32_e32 v15, v65
	v_add_f32_e32 v15, v15, v65
	v_cmp_lt_f32_e32 vcc, s5, v15
	s_cbranch_vccz .LBB0_709
; __device__ __forceinline__ unsigned pk2(float lo, float hi) { f32x2 v = {lo, hi}; bf16x2_t b = __builtin_convertvector(v, bf16x2_t); return __builtin_bit_cast(unsigned, b); }
; __device__ __forceinline__ float hmax(float m) { auto rr = __builtin_amdgcn_permlane32_swap(__float_as_uint(m), __float_as_uint(m), false, false); return fmaxf(__uint_as_float(rr[0]), __uint_as_float(rr[1])); }
; template <int TYPE, int ND0, int KSTR> __device__ __forceinline__ void tile(LAS unsigned char* lds, int buf, int t, int w_lo, int w_hi, int n, int qrel, int lane, int r32, int hi,
;         const bf16x8 (&qr)[ND0], float& m_run, float& l_run, f32x16& o0, f32x16& o1, f32x16& negm) {
;     ...
;     if (__builtin_amdgcn_ballot_w64(lrow > 1099511627776.0f) != 0ull) {
;         float pm = fmaxf(p0[0], p1[0]);
; #pragma unroll
;         for (int r = 1; r < 16; ++r) pm = fmaxf(pm, fmaxf(p0[r], p1[r]));
;         pm = hmax(pm);
;         const float dl = (lrow > 1099511627776.0f) ? __builtin_amdgcn_logf(pm) : 0.f;
;         const float sc = __builtin_amdgcn_exp2f(-dl);
;         m_run += dl; l_run *= sc; ls *= sc;
; #pragma unroll
;         for (int r = 0; r < 16; ++r) { p0[r] *= sc; p1[r] *= sc; o0[r] *= sc; o1[r] *= sc; negm[r] = -m_run; }
;     }
;     l_run += ls;
; #pragma unroll
;     for (int ks = 0; ks < 4; ++ks) {
;         u32x4 pw;
;         if (ks < 2) { pw.x = pk2(p0[8 * ks], p0[8 * ks + 1]); pw.y = pk2(p0[8 * ks + 2], p0[8 * ks + 3]); pw.z = pk2(p0[8 * ks + 4], p0[8 * ks + 5]); pw.w = pk2(p0[8 * ks + 6], p0[8 * ks + 7]); }
;         else { const int k2 = ks - 2; pw.x = pk2(p1[8 * k2], p1[8 * k2 + 1]); pw.y = pk2(p1[8 * k2 + 2], p1[8 * k2 + 3]); pw.z = pk2(p1[8 * k2 + 4], p1[8 * k2 + 5]); pw.w = pk2(p1[8 * k2 + 6], p1[8 * k2 + 7]); }
;         const bf16x8 pb = __builtin_bit_cast(bf16x8, pw);
;         const bf16x8 va0 = __builtin_shufflevector(vf[ks][0], vf[ks][1], 0, 1, 2, 3, 4, 5, 6, 7), va1 = __builtin_shufflevector(vf[ks][2], vf[ks][3], 0, 1, 2, 3, 4, 5, 6, 7);
;         o0 = __builtin_amdgcn_mfma_f32_32x32x16_bf16(va0, pb, o0, 0, 0, 0);
;         o1 = __builtin_amdgcn_mfma_f32_32x32x16_bf16(va1, pb, o1, 0, 0, 0);
;     }
	v_max_f32_e32 v15, v186, v186
	v_max_f32_e32 v48, v0, v0
	v_max_f32_e32 v15, v48, v15
	v_max_f32_e32 v48, v64, v64
	v_max_f32_e32 v49, v80, v80
	v_max_f32_e32 v48, v49, v48
	v_max_f32_e32 v49, v188, v188
	v_max_f32_e32 v50, v196, v196
	v_max3_f32 v15, v182, v14, v15
	v_max_f32_e32 v49, v50, v49
	v_max3_f32 v15, v15, v48, v49
	v_max_f32_e32 v48, v66, v66
	v_max_f32_e32 v49, v82, v82
	v_max_f32_e32 v48, v49, v48
	v_max_f32_e32 v49, v190, v190
	v_max_f32_e32 v50, v198, v198
	v_max_f32_e32 v49, v50, v49
	v_max3_f32 v15, v15, v48, v49
	v_max_f32_e32 v48, v70, v70
	v_max_f32_e32 v49, v184, v184
	v_max_f32_e32 v48, v49, v48
	v_max_f32_e32 v49, v194, v194
	v_max_f32_e32 v50, v202, v202
	v_max_f32_e32 v49, v50, v49
	v_max3_f32 v15, v15, v48, v49
	v_max_f32_e32 v48, v68, v68
	v_max_f32_e32 v49, v84, v84
	v_max_f32_e32 v48, v49, v48
	v_max_f32_e32 v49, v192, v192
	v_max_f32_e32 v50, v200, v200
	v_max_f32_e32 v49, v50, v49
	v_max3_f32 v15, v15, v48, v49
	v_max_f32_e32 v48, v72, v72
	v_max_f32_e32 v49, v86, v86
	v_max_f32_e32 v48, v49, v48
	v_max_f32_e32 v49, v90, v90
	v_max_f32_e32 v50, v204, v204
	v_max_f32_e32 v49, v50, v49
	v_max3_f32 v15, v15, v48, v49
	v_max_f32_e32 v48, v74, v74
	v_max_f32_e32 v49, v88, v88
	v_max_f32_e32 v48, v49, v48
	v_max_f32_e32 v49, v92, v92
	v_max_f32_e32 v50, v206, v206
	v_max_f32_e32 v49, v50, v49
	v_max3_f32 v15, v15, v48, v49
	v_max_f32_e32 v48, v76, v76
	v_max_f32_e32 v49, v78, v78
	v_max_f32_e32 v48, v49, v48
	v_max_f32_e32 v49, v94, v94
	v_max_f32_e32 v50, v220, v220
	v_max_f32_e32 v49, v50, v49
	v_max3_f32 v15, v15, v48, v49
	v_mov_b32_e32 v48, v15
	s_nop 1
	v_permlane32_swap_b32_e32 v15, v48
	v_max_f32_e32 v48, v48, v48
	v_max_f32_e32 v15, v15, v15
	v_max_f32_e32 v15, v15, v48
	v_log_f32_e32 v15, v15
	v_mov_b32_e32 v167, v222
	v_mov_b32_e32 v79, v220
	v_mov_b32_e32 v89, v206
	v_cndmask_b32_e32 v15, 0, v15, vcc
	v_exp_f32_e64 v208, -v15
	v_add_f32_e32 v171, v171, v15
	v_mov_b32_e32 v87, v204
	v_mov_b32_e32 v85, v200
	v_mov_b32_e32 v185, v202
	v_mov_b32_e32 v83, v198
	v_mov_b32_e32 v81, v196
	v_mov_b32_e32 v183, v0
	v_mov_b32_e32 v77, v94
	v_mov_b32_e32 v75, v92
	v_mov_b32_e32 v73, v90
	v_mov_b32_e32 v69, v192
	v_mov_b32_e32 v71, v194
	v_mov_b32_e32 v67, v190
	v_mov_b32_e32 v65, v188
	v_mov_b32_e32 v15, v186
	v_xor_b32_e32 v48, 0x80000000, v171
	v_pk_mul_f32 v[78:79], v[78:79], v[208:209] op_sel_hi:[1,0]
	v_pk_mul_f32 v[88:89], v[88:89], v[208:209] op_sel_hi:[1,0]
	v_pk_mul_f32 v[86:87], v[86:87], v[208:209] op_sel_hi:[1,0]
	v_pk_mul_f32 v[84:85], v[84:85], v[208:209] op_sel_hi:[1,0]
	v_pk_mul_f32 v[184:185], v[184:185], v[208:209] op_sel_hi:[1,0]
	v_pk_mul_f32 v[82:83], v[82:83], v[208:209] op_sel_hi:[1,0]
	v_pk_mul_f32 v[80:81], v[80:81], v[208:209] op_sel_hi:[1,0]
	v_pk_mul_f32 v[182:183], v[182:183], v[208:209] op_sel_hi:[1,0]
	v_pk_mul_f32 v[76:77], v[76:77], v[208:209] op_sel_hi:[1,0]
	v_pk_mul_f32 v[74:75], v[74:75], v[208:209] op_sel_hi:[1,0]
	v_pk_mul_f32 v[72:73], v[72:73], v[208:209] op_sel_hi:[1,0]
	v_pk_mul_f32 v[68:69], v[68:69], v[208:209] op_sel_hi:[1,0]
	v_pk_mul_f32 v[70:71], v[70:71], v[208:209] op_sel_hi:[1,0]
	v_pk_mul_f32 v[66:67], v[66:67], v[208:209] op_sel_hi:[1,0]
	v_pk_mul_f32 v[64:65], v[64:65], v[208:209] op_sel_hi:[1,0]
	v_pk_mul_f32 v[14:15], v[14:15], v[208:209] op_sel_hi:[1,0]
	v_pk_mul_f32 v[166:167], v[166:167], v[208:209] op_sel_hi:[1,0]
	v_pk_mul_f32 v[46:47], v[46:47], v[208:209] op_sel_hi:[1,0]
	v_pk_mul_f32 v[44:45], v[44:45], v[208:209] op_sel_hi:[1,0]
	v_pk_mul_f32 v[42:43], v[42:43], v[208:209] op_sel_hi:[1,0]
	v_pk_mul_f32 v[40:41], v[40:41], v[208:209] op_sel_hi:[1,0]
	v_pk_mul_f32 v[38:39], v[38:39], v[208:209] op_sel_hi:[1,0]
	v_pk_mul_f32 v[36:37], v[36:37], v[208:209] op_sel_hi:[1,0]
	v_pk_mul_f32 v[34:35], v[34:35], v[208:209] op_sel_hi:[1,0]
	v_pk_mul_f32 v[32:33], v[32:33], v[208:209] op_sel_hi:[1,0]
	v_pk_mul_f32 v[30:31], v[30:31], v[208:209] op_sel_hi:[1,0]
	v_pk_mul_f32 v[28:29], v[28:29], v[208:209] op_sel_hi:[1,0]
	v_pk_mul_f32 v[26:27], v[26:27], v[208:209] op_sel_hi:[1,0]
	v_pk_mul_f32 v[24:25], v[24:25], v[208:209] op_sel_hi:[1,0]
	v_pk_mul_f32 v[22:23], v[22:23], v[208:209] op_sel_hi:[1,0]
	v_pk_mul_f32 v[20:21], v[20:21], v[208:209] op_sel_hi:[1,0]
	v_pk_mul_f32 v[18:19], v[18:19], v[208:209] op_sel_hi:[1,0]
	v_pk_mul_f32 v[16:17], v[16:17], v[208:209] op_sel_hi:[1,0]
	v_mov_b32_e32 v49, v48
	v_mov_b32_e32 v50, v48
	v_mov_b32_e32 v51, v48
	v_mov_b32_e32 v52, v48
	v_mov_b32_e32 v53, v48
	v_mov_b32_e32 v54, v48
	v_mov_b32_e32 v55, v48
	v_mov_b32_e32 v56, v48
	v_mov_b32_e32 v57, v48
	v_mov_b32_e32 v58, v48
	v_mov_b32_e32 v59, v48
	v_mov_b32_e32 v60, v48
	v_mov_b32_e32 v61, v48
	v_mov_b32_e32 v62, v48
	v_mov_b32_e32 v63, v48
	v_mov_b32_e32 v186, v15
	v_mov_b32_e32 v188, v65
	v_mov_b32_e32 v190, v67
	v_mov_b32_e32 v194, v71
	v_mov_b32_e32 v192, v69
	v_mov_b32_e32 v90, v73
	v_mov_b32_e32 v92, v75
	v_mov_b32_e32 v94, v77
	v_mov_b32_e32 v0, v183
	v_mov_b32_e32 v196, v81
	v_mov_b32_e32 v198, v83
	v_mov_b32_e32 v202, v185
	v_mov_b32_e32 v200, v85
	v_mov_b32_e32 v204, v87
	v_mov_b32_e32 v206, v89
	v_mov_b32_e32 v220, v79
	v_mov_b32_e32 v222, v167
.LBB0_709:
	v_cvt_pk_bf16_f32 v80, v84, v200
	v_cvt_pk_bf16_f32 v81, v86, v204
	v_cvt_pk_bf16_f32 v82, v88, v206
	v_cvt_pk_bf16_f32 v83, v78, v220
	v_cvt_pk_bf16_f32 v64, v68, v192
	v_cvt_pk_bf16_f32 v65, v72, v90
	v_cvt_pk_bf16_f32 v66, v74, v92
	v_cvt_pk_bf16_f32 v67, v76, v94
	v_add_f32_e32 v166, v166, v222
	v_mfma_f32_32x32x16_bf16 v[32:47], v[152:155], v[80:83], v[32:47]
	v_mfma_f32_32x32x16_bf16 v[16:31], v[148:151], v[80:83], v[16:31]
	s_waitcnt lgkmcnt(2)
	v_mfma_f32_32x32x16_bf16 v[32:47], v[112:115], v[64:67], v[32:47]
	s_waitcnt lgkmcnt(0)
	v_mfma_f32_32x32x16_bf16 v[16:31], v[108:111], v[64:67], v[16:31]
